# grid barriers: after publishing the per-XCC release the leader waits only for its own invalidate (vmcnt(1)), not for the release atomic's acknowledgement
# speedup vs baseline: 1.0019x; 1.0003x over previous
; __device__ __forceinline__ unsigned xb_ld(unsigned* p)              { return __hip_atomic_load(p, __ATOMIC_RELAXED, __HIP_MEMORY_SCOPE_AGENT); }
; __device__ __forceinline__ unsigned xb_add(unsigned* p, unsigned v) { return __hip_atomic_fetch_add(p, v, __ATOMIC_RELAXED, __HIP_MEMORY_SCOPE_AGENT); }
; #define XB_SPIN(cond, bar) do { unsigned _sp = 0; while (cond) { __builtin_amdgcn_s_sleep(1); \
;     if ((++_sp & 255u) == 0u) { if (xb_ld(&(bar)[XB_TMO])) break; if (_sp > XB_SPIN_CAP) { atomicAdd(&(bar)[XB_TMO], 1u); break; } } } } while (0)
; __device__ __forceinline__ void xcd_barrier(const XcdBarrier& b, const int WID) {
;     ...
;             if (og + 1u == (tg + 1u) * nx) xb_add(&bar[XB_TOPGEN], 1u);
;             else XB_SPIN(xb_ld(&bar[XB_TOPGEN]) == tg, bar);
;             __builtin_amdgcn_fence(__ATOMIC_ACQUIRE, "agent");
;             xb_add(&bar[XB_XGEN(b.x)], 1u);
;             asm volatile("s_waitcnt vmcnt(0)" ::: "memory");
.Lgb_topdone:
	s_waitcnt vmcnt(0)
	buffer_inv sc1
	v_mov_b32_e32 v2, s9
	s_nop 0
	global_atomic_add v2, v3, s[4:5]
	s_waitcnt vmcnt(1)
	s_branch .Lgb_done

; __device__ __forceinline__ unsigned xb_add(unsigned* p, unsigned v) { return __hip_atomic_fetch_add(p, v, __ATOMIC_RELAXED, __HIP_MEMORY_SCOPE_AGENT); }
; __device__ __forceinline__ void xcd_barrier(const XcdBarrier& b, const int WID) {
;     ...
;             xb_add(&bar[XB_XGEN(b.x)], 1u);
;             asm volatile("s_waitcnt vmcnt(0)" ::: "memory");
.LBB0_146:
	s_or_b64 exec, exec, s[10:11]
	s_waitcnt vmcnt(1)

; __device__ __forceinline__ unsigned xb_add(unsigned* p, unsigned v) { return __hip_atomic_fetch_add(p, v, __ATOMIC_RELAXED, __HIP_MEMORY_SCOPE_AGENT); }
; __device__ __forceinline__ void xcd_barrier(const XcdBarrier& b, const int WID) {
;     ...
;             xb_add(&bar[XB_XGEN(b.x)], 1u);
;             asm volatile("s_waitcnt vmcnt(0)" ::: "memory");
.LBB0_209:
	s_or_b64 exec, exec, s[8:9]
	s_waitcnt vmcnt(1)

; __device__ __forceinline__ unsigned xb_add(unsigned* p, unsigned v) { return __hip_atomic_fetch_add(p, v, __ATOMIC_RELAXED, __HIP_MEMORY_SCOPE_AGENT); }
; __device__ __forceinline__ void xcd_barrier(const XcdBarrier& b, const int WID) {
;     ...
;             xb_add(&bar[XB_XGEN(b.x)], 1u);
;             asm volatile("s_waitcnt vmcnt(0)" ::: "memory");
.LBB0_654:
	s_or_b64 exec, exec, s[4:5]
	s_waitcnt vmcnt(1)
